# DSA attention PV loop: two V-chunk gathers in flight (second landing set v[94:125]), loop unrolled x2, counted vmcnt(15..8)
# speedup vs baseline: 1.0161x; 1.0054x over previous
; #define LAS __attribute__((address_space(3)))
; __device__ __forceinline__ void dsa_phase(Frame& F) {
;     ...
;                 f32x4 sv[4]; f32x4 mx = {-INFINITY, -INFINITY, -INFINITY, -INFINITY};
; #pragma unroll
;                 for (int jj = 0; jj < 4; ++jj) { if (lane + 64 * jj < nsel) sv[jj] = *(const LAS f32x4*)(Pw + (lane + 64 * jj) * 4); else sv[jj] = (f32x4){-INFINITY, -INFINITY, -INFINITY, -INFINITY};
; #pragma unroll
;                     for (int hh = 0; hh < 4; ++hh) mx[hh] = fmaxf(mx[hh], sv[jj][hh]); }
;                 f32x4 sm = {0.f, 0.f, 0.f, 0.f};
; #pragma unroll
;                 for (int hh = 0; hh < 4; ++hh) { mx[hh] = wave_max(mx[hh]);
; #pragma unroll
;                     for (int jj = 0; jj < 4; ++jj) { sv[jj][hh] = __expf(sv[jj][hh] - mx[hh]); sm[hh] += sv[jj][hh]; }
;                     sm[hh] = 1.f / wave_sum(sm[hh]); }
.LBB0_1166:
	s_xor_b64 s[24:25], s[26:27], -1
	s_and_saveexec_b64 s[26:27], s[10:11]
	s_xor_b64 s[26:27], exec, s[26:27]
	s_or_saveexec_b64 s[26:27], s[26:27]
	v_mov_b32_e32 v36, 0xff800000
	v_mov_b32_e32 v37, 0xff800000
	v_mov_b32_e32 v38, 0xff800000
	v_mov_b32_e32 v39, 0xff800000
	s_xor_b64 exec, exec, s[26:27]
	ds_read_b128 v[36:39], v210 offset:15360
	s_or_b64 exec, exec, s[26:27]
	s_and_saveexec_b64 s[26:27], s[12:13]
	s_xor_b64 s[26:27], exec, s[26:27]
	s_or_saveexec_b64 s[26:27], s[26:27]
	s_waitcnt vmcnt(8)
	v_mov_b32_e32 v40, 0xff800000
	v_mov_b32_e32 v41, 0xff800000
	v_mov_b32_e32 v42, 0xff800000
	v_mov_b32_e32 v43, 0xff800000
	s_xor_b64 exec, exec, s[26:27]
	ds_read_b128 v[40:43], v211 offset:15360
	s_or_b64 exec, exec, s[26:27]
	s_and_saveexec_b64 s[26:27], s[14:15]
	s_xor_b64 s[26:27], exec, s[26:27]
	s_or_saveexec_b64 s[26:27], s[26:27]
	v_mov_b32_e32 v44, 0xff800000
	v_mov_b32_e32 v45, 0xff800000
	v_mov_b32_e32 v46, 0xff800000
	v_mov_b32_e32 v47, 0xff800000
	s_xor_b64 exec, exec, s[26:27]
	ds_read_b128 v[44:47], v212 offset:15360
	s_or_b64 exec, exec, s[26:27]
	s_and_saveexec_b64 s[26:27], s[16:17]
	s_xor_b64 s[26:27], exec, s[26:27]
	s_or_saveexec_b64 s[26:27], s[26:27]
	v_mov_b32_e32 v48, 0xff800000
	v_mov_b32_e32 v49, 0xff800000
	v_mov_b32_e32 v50, 0xff800000
	v_mov_b32_e32 v51, 0xff800000
	s_xor_b64 exec, exec, s[26:27]
	ds_read_b128 v[48:51], v213 offset:15360
	s_or_b64 exec, exec, s[26:27]
	s_waitcnt lgkmcnt(0)
	v_max3_f32 v32, v36, s77, v40
	v_max3_f32 v32, v32, v44, v48
	v_mov_b32_e32 v52, 0
	v_max3_f32 v33, v37, s77, v41
	v_max3_f32 v33, v33, v45, v49
	v_mov_b32_dpp v52, v32 quad_perm:[1,0,3,2] row_mask:0xf bank_mask:0xf
	v_max_f32_e32 v52, v52, v52
	v_max_f32_e32 v32, v32, v52
	v_mov_b32_e32 v52, 0
	v_max3_f32 v34, v38, s77, v42
	v_max3_f32 v34, v34, v46, v50
	v_mov_b32_dpp v52, v32 quad_perm:[2,3,0,1] row_mask:0xf bank_mask:0xf
	v_max_f32_e32 v52, v52, v52
	v_max_f32_e32 v32, v32, v52
	v_mov_b32_e32 v52, 0
	v_max3_f32 v35, v39, s77, v43
	v_max3_f32 v53, v35, v47, v51
	v_mov_b32_dpp v52, v32 row_half_mirror row_mask:0xf bank_mask:0xf
	v_max_f32_e32 v52, v52, v52
	v_max_f32_e32 v32, v32, v52
	v_mov_b32_e32 v52, 0
	v_mov_b32_e32 v35, 0
	v_mov_b32_e32 v63, 0
	v_mov_b32_dpp v52, v32 row_mirror row_mask:0xf bank_mask:0xf
	v_max_f32_e32 v52, v52, v52
	v_max_f32_e32 v32, v32, v52
	v_mov_b32_e32 v52, v32
	v_mov_b32_e32 v62, 0
	v_mov_b32_e32 v61, 0
	v_mov_b32_dpp v52, v52 row_bcast:15 row_mask:0xa bank_mask:0xf
	v_max_f32_e32 v52, v52, v52
	v_max_f32_e32 v32, v32, v52
	v_mov_b32_e32 v52, v32
	v_mov_b32_e32 v60, 0
	v_mov_b32_e32 v59, 0
	v_mov_b32_dpp v52, v52 row_bcast:31 row_mask:0xc bank_mask:0xf
	v_max_f32_e32 v52, v52, v52
	v_max_f32_e32 v32, v32, v52
	v_mov_b32_e32 v52, 0
	v_readlane_b32 s26, v32, 63
	v_mov_b32_e32 v58, 0
	v_mov_b32_e32 v57, 0
	v_subrev_f32_e32 v32, s26, v36
	v_mul_f32_e32 v32, 0x3fb8aa3b, v32
	v_subrev_f32_e32 v36, s26, v40
	v_exp_f32_e32 v32, v32
	v_mul_f32_e32 v36, 0x3fb8aa3b, v36
	v_subrev_f32_e32 v40, s26, v44
	v_exp_f32_e32 v36, v36
	v_mul_f32_e32 v40, 0x3fb8aa3b, v40
	v_subrev_f32_e32 v44, s26, v48
	v_exp_f32_e32 v40, v40
	v_mul_f32_e32 v44, 0x3fb8aa3b, v44
	v_exp_f32_e32 v44, v44
	v_add_f32_e32 v48, 0, v32
	v_add_f32_e32 v48, v36, v48
	v_add_f32_e32 v48, v40, v48
	v_add_f32_e32 v48, v44, v48
	s_nop 1
	v_add_f32_dpp v48, v48, v48 quad_perm:[1,0,3,2] row_mask:0xf bank_mask:0xf bound_ctrl:1
	s_nop 1
	v_add_f32_dpp v48, v48, v48 quad_perm:[2,3,0,1] row_mask:0xf bank_mask:0xf bound_ctrl:1
	s_nop 1
	v_add_f32_dpp v48, v48, v48 row_half_mirror row_mask:0xf bank_mask:0xf bound_ctrl:1
	s_nop 1
	v_add_f32_dpp v48, v48, v48 row_mirror row_mask:0xf bank_mask:0xf bound_ctrl:1
	s_nop 1
	v_mov_b32_dpp v52, v48 row_bcast:15 row_mask:0xa bank_mask:0xf
	v_add_f32_e32 v48, v48, v52
	v_mov_b32_e32 v52, 0
	s_nop 1
	v_mov_b32_dpp v52, v48 row_bcast:31 row_mask:0xc bank_mask:0xf
	v_add_f32_e32 v48, v48, v52
	s_nop 0
	v_readlane_b32 s66, v48, 63
	s_nop 1
	v_div_scale_f32 v48, s[26:27], s66, s66, 1.0
	v_rcp_f32_e32 v52, v48
	s_nop 0
	v_fma_f32 v54, -v48, v52, 1.0
	v_fmac_f32_e32 v52, v54, v52
	v_div_scale_f32 v54, vcc, 1.0, s66, 1.0
	v_mul_f32_e32 v55, v54, v52
	v_fma_f32 v56, -v48, v55, v54
	v_fmac_f32_e32 v55, v56, v52
	v_fma_f32 v48, -v48, v55, v54
	v_mov_b32_e32 v54, 0
	v_div_fmas_f32 v48, v48, v52, v55
	v_div_fixup_f32 v48, v48, s66, 1.0
	v_mov_b32_dpp v54, v33 quad_perm:[1,0,3,2] row_mask:0xf bank_mask:0xf
	v_max_f32_e32 v54, v54, v54
	v_max_f32_e32 v33, v33, v54
	v_mov_b32_e32 v54, 0
	v_mul_f32_e32 v32, v32, v48
	s_nop 0
	v_mov_b32_dpp v54, v33 quad_perm:[2,3,0,1] row_mask:0xf bank_mask:0xf
	v_max_f32_e32 v54, v54, v54
	v_max_f32_e32 v33, v33, v54
	v_mov_b32_e32 v54, 0
	s_nop 1
	v_mov_b32_dpp v54, v33 row_half_mirror row_mask:0xf bank_mask:0xf
	v_max_f32_e32 v54, v54, v54
	v_max_f32_e32 v33, v33, v54
	v_mov_b32_e32 v54, 0
	s_nop 1
	v_mov_b32_dpp v54, v33 row_mirror row_mask:0xf bank_mask:0xf
	v_max_f32_e32 v54, v54, v54
	v_max_f32_e32 v33, v33, v54
	v_mov_b32_e32 v54, v33
	s_nop 1
	v_mov_b32_dpp v54, v54 row_bcast:15 row_mask:0xa bank_mask:0xf
	v_max_f32_e32 v54, v54, v54
	v_max_f32_e32 v33, v33, v54
	v_mov_b32_e32 v54, v33
	s_nop 1
	v_mov_b32_dpp v54, v54 row_bcast:31 row_mask:0xc bank_mask:0xf
	v_max_f32_e32 v54, v54, v54
	v_max_f32_e32 v33, v33, v54
	v_mov_b32_e32 v54, 0
	v_readlane_b32 s26, v33, 63
	s_nop 1
	v_subrev_f32_e32 v33, s26, v37
	v_mul_f32_e32 v33, 0x3fb8aa3b, v33
	v_subrev_f32_e32 v37, s26, v41
	v_exp_f32_e32 v33, v33
	v_mul_f32_e32 v37, 0x3fb8aa3b, v37
	v_subrev_f32_e32 v41, s26, v45
	v_exp_f32_e32 v37, v37
	v_mul_f32_e32 v41, 0x3fb8aa3b, v41
	v_subrev_f32_e32 v45, s26, v49
	v_exp_f32_e32 v41, v41
; __device__ __forceinline__ void dsa_phase(Frame& F) {
;     ...
;                 for (int hh = 0; hh < 4; ++hh) { mx[hh] = wave_max(mx[hh]);
; #pragma unroll
;                     for (int jj = 0; jj < 4; ++jj) { sv[jj][hh] = __expf(sv[jj][hh] - mx[hh]); sm[hh] += sv[jj][hh]; }
;                     sm[hh] = 1.f / wave_sum(sm[hh]); }
	v_mul_f32_e32 v45, 0x3fb8aa3b, v45
	v_exp_f32_e32 v45, v45
	v_add_f32_e32 v49, 0, v33
	v_add_f32_e32 v49, v37, v49
	v_add_f32_e32 v49, v41, v49
	v_add_f32_e32 v49, v45, v49
	s_nop 1
	v_add_f32_dpp v49, v49, v49 quad_perm:[1,0,3,2] row_mask:0xf bank_mask:0xf bound_ctrl:1
	s_nop 1
	v_add_f32_dpp v49, v49, v49 quad_perm:[2,3,0,1] row_mask:0xf bank_mask:0xf bound_ctrl:1
	s_nop 1
	v_add_f32_dpp v49, v49, v49 row_half_mirror row_mask:0xf bank_mask:0xf bound_ctrl:1
	s_nop 1
	v_add_f32_dpp v49, v49, v49 row_mirror row_mask:0xf bank_mask:0xf bound_ctrl:1
	s_nop 1
	v_mov_b32_dpp v54, v49 row_bcast:15 row_mask:0xa bank_mask:0xf
	v_add_f32_e32 v49, v49, v54
	v_mov_b32_e32 v54, 0
	s_nop 1
	v_mov_b32_dpp v54, v49 row_bcast:31 row_mask:0xc bank_mask:0xf
	v_add_f32_e32 v49, v49, v54
	s_nop 0
	v_readlane_b32 s67, v49, 63
	s_nop 1
	v_div_scale_f32 v49, s[26:27], s67, s67, 1.0
	v_rcp_f32_e32 v54, v49
	s_nop 0
	v_fma_f32 v52, -v49, v54, 1.0
	v_fmac_f32_e32 v54, v52, v54
	v_div_scale_f32 v52, vcc, 1.0, s67, 1.0
	v_mul_f32_e32 v55, v52, v54
	v_fma_f32 v56, -v49, v55, v52
	v_fmac_f32_e32 v55, v56, v54
	v_fma_f32 v49, -v49, v55, v52
	v_mov_b32_e32 v52, 0
	v_div_fmas_f32 v49, v49, v54, v55
	v_div_fixup_f32 v49, v49, s67, 1.0
	v_mov_b32_dpp v52, v34 quad_perm:[1,0,3,2] row_mask:0xf bank_mask:0xf
	v_max_f32_e32 v52, v52, v52
	v_max_f32_e32 v34, v34, v52
	v_mov_b32_e32 v52, 0
	s_nop 1
	v_mov_b32_dpp v52, v34 quad_perm:[2,3,0,1] row_mask:0xf bank_mask:0xf
	v_max_f32_e32 v52, v52, v52
	v_max_f32_e32 v34, v34, v52
	v_mov_b32_e32 v52, 0
	s_nop 1
	v_mov_b32_dpp v52, v34 row_half_mirror row_mask:0xf bank_mask:0xf
	v_max_f32_e32 v52, v52, v52
	v_max_f32_e32 v34, v34, v52
	v_mov_b32_e32 v52, 0
	s_nop 1
	v_mov_b32_dpp v52, v34 row_mirror row_mask:0xf bank_mask:0xf
	v_max_f32_e32 v52, v52, v52
	v_max_f32_e32 v34, v34, v52
	v_mov_b32_e32 v52, v34
	s_nop 1
	v_mov_b32_dpp v52, v52 row_bcast:15 row_mask:0xa bank_mask:0xf
	v_max_f32_e32 v52, v52, v52
	v_max_f32_e32 v34, v34, v52
	v_mov_b32_e32 v52, v34
	s_nop 1
	v_mov_b32_dpp v52, v52 row_bcast:31 row_mask:0xc bank_mask:0xf
	v_max_f32_e32 v52, v52, v52
	v_max_f32_e32 v34, v34, v52
	v_mov_b32_e32 v52, 0
	v_readlane_b32 s26, v34, 63
	s_nop 1
	v_subrev_f32_e32 v34, s26, v38
	v_mul_f32_e32 v34, 0x3fb8aa3b, v34
	v_subrev_f32_e32 v38, s26, v42
	v_exp_f32_e32 v34, v34
	v_mul_f32_e32 v38, 0x3fb8aa3b, v38
	v_subrev_f32_e32 v42, s26, v46
	v_exp_f32_e32 v38, v38
	v_mul_f32_e32 v42, 0x3fb8aa3b, v42
	v_subrev_f32_e32 v46, s26, v50
	v_exp_f32_e32 v42, v42
	v_mul_f32_e32 v46, 0x3fb8aa3b, v46
	v_exp_f32_e32 v46, v46
	v_add_f32_e32 v50, 0, v34
	v_add_f32_e32 v50, v38, v50
	v_add_f32_e32 v50, v42, v50
	v_add_f32_e32 v50, v46, v50
	s_nop 1
	v_add_f32_dpp v50, v50, v50 quad_perm:[1,0,3,2] row_mask:0xf bank_mask:0xf bound_ctrl:1
	s_nop 1
	v_add_f32_dpp v50, v50, v50 quad_perm:[2,3,0,1] row_mask:0xf bank_mask:0xf bound_ctrl:1
	s_nop 1
	v_add_f32_dpp v50, v50, v50 row_half_mirror row_mask:0xf bank_mask:0xf bound_ctrl:1
	s_nop 1
	v_add_f32_dpp v50, v50, v50 row_mirror row_mask:0xf bank_mask:0xf bound_ctrl:1
	s_nop 1
	v_mov_b32_dpp v52, v50 row_bcast:15 row_mask:0xa bank_mask:0xf
	v_add_f32_e32 v50, v50, v52
	v_mov_b32_e32 v52, 0
	s_nop 1
	v_mov_b32_dpp v52, v50 row_bcast:31 row_mask:0xc bank_mask:0xf
	v_add_f32_e32 v50, v50, v52
	s_nop 0
	v_readlane_b32 s66, v50, 63
	s_nop 1
	v_div_scale_f32 v50, s[26:27], s66, s66, 1.0
	v_rcp_f32_e32 v52, v50
	s_nop 0
	v_fma_f32 v54, -v50, v52, 1.0
	v_fmac_f32_e32 v52, v54, v52
	v_div_scale_f32 v54, vcc, 1.0, s66, 1.0
	v_mul_f32_e32 v55, v54, v52
	v_fma_f32 v56, -v50, v55, v54
	v_fmac_f32_e32 v55, v56, v52
	v_fma_f32 v50, -v50, v55, v54
	v_mov_b32_e32 v54, 0
	v_div_fmas_f32 v50, v50, v52, v55
	v_div_fixup_f32 v50, v50, s66, 1.0
	v_mov_b32_dpp v54, v53 quad_perm:[1,0,3,2] row_mask:0xf bank_mask:0xf
	v_max_f32_e32 v54, v54, v54
	v_max_f32_e32 v53, v53, v54
	v_mov_b32_e32 v54, 0
	s_nop 1
	v_mov_b32_dpp v54, v53 quad_perm:[2,3,0,1] row_mask:0xf bank_mask:0xf
	v_max_f32_e32 v54, v54, v54
	v_max_f32_e32 v53, v53, v54
	v_mov_b32_e32 v54, 0
	s_nop 1
	v_mov_b32_dpp v54, v53 row_half_mirror row_mask:0xf bank_mask:0xf
	v_max_f32_e32 v54, v54, v54
	v_max_f32_e32 v53, v53, v54
	v_mov_b32_e32 v54, 0
	s_nop 1
	v_mov_b32_dpp v54, v53 row_mirror row_mask:0xf bank_mask:0xf
	v_max_f32_e32 v54, v54, v54
	v_max_f32_e32 v53, v53, v54
	v_mov_b32_e32 v54, v53
	s_nop 1
	v_mov_b32_dpp v54, v54 row_bcast:15 row_mask:0xa bank_mask:0xf
	v_max_f32_e32 v54, v54, v54
	v_max_f32_e32 v53, v53, v54
	v_mov_b32_e32 v54, v53
	s_nop 1
	v_mov_b32_dpp v54, v54 row_bcast:31 row_mask:0xc bank_mask:0xf
	v_max_f32_e32 v54, v54, v54
	v_max_f32_e32 v53, v53, v54
	v_mov_b32_e32 v54, 0
	v_readlane_b32 s26, v53, 63
	s_nop 1
	v_subrev_f32_e32 v39, s26, v39
	v_mul_f32_e32 v39, 0x3fb8aa3b, v39
	v_subrev_f32_e32 v43, s26, v43
	v_exp_f32_e32 v39, v39
	v_mul_f32_e32 v43, 0x3fb8aa3b, v43
	v_subrev_f32_e32 v47, s26, v47
	v_exp_f32_e32 v43, v43
	v_mul_f32_e32 v47, 0x3fb8aa3b, v47
	v_subrev_f32_e32 v51, s26, v51
	v_exp_f32_e32 v47, v47
	v_mul_f32_e32 v51, 0x3fb8aa3b, v51
	v_exp_f32_e32 v51, v51
	v_add_f32_e32 v53, 0, v39
	v_add_f32_e32 v53, v43, v53
	v_add_f32_e32 v53, v47, v53
	v_add_f32_e32 v53, v51, v53
	s_nop 1
	v_add_f32_dpp v53, v53, v53 quad_perm:[1,0,3,2] row_mask:0xf bank_mask:0xf bound_ctrl:1
	s_nop 1
	v_add_f32_dpp v53, v53, v53 quad_perm:[2,3,0,1] row_mask:0xf bank_mask:0xf bound_ctrl:1
	s_nop 1
	v_add_f32_dpp v53, v53, v53 row_half_mirror row_mask:0xf bank_mask:0xf bound_ctrl:1
	s_nop 1
	v_add_f32_dpp v53, v53, v53 row_mirror row_mask:0xf bank_mask:0xf bound_ctrl:1
	s_nop 1
	v_mov_b32_dpp v54, v53 row_bcast:15 row_mask:0xa bank_mask:0xf
	v_add_f32_e32 v53, v53, v54
; __device__ __forceinline__ unsigned f2bf(float f) { unsigned u = __builtin_bit_cast(unsigned, f); return (u + 0x7fffu + ((u >> 16) & 1u)) >> 16; }
; #define DSA_GATHER(c, g_, off_) do { _Pragma("unroll") for (int i = 0; i < 8; ++i) { const unsigned kidx = ixl[(c) * 32 + kq + 4 * i]; \
;                 gr[i] = *(const u32x4*)(KV2 + ((size_t)kidx * 2 + (g_)) * 256 + (off_) + 8 * col); } } while (0)
; #define DSA_PUT() do { _Pragma("unroll") for (int i = 0; i < 8; ++i) *(LAS u32x4*)(vst + (kq + 4 * i) * 272 + col * 16) = gr[i]; } while (0)
; __device__ __forceinline__ void dsa_phase(Frame& F) {
;     ...
; #pragma unroll
;                 for (int jj = 0; jj < 4; ++jj)
; #pragma unroll
;                     for (int hh = 0; hh < 4; ++hh) Pb[hh * 256 + lane + 64 * jj] = (unsigned short)f2bf(sv[jj][hh] * sm[hh]);
;                 f32x4 oacc[8];
; #pragma unroll
;                 for (int db = 0; db < 8; ++db) oacc[db] = (f32x4){0.f, 0.f, 0.f, 0.f};
;                 const int tq = col >> 2, tp = col & 3;
;                 for (int c = 0; c < nch; ++c) {
;                     DSA_PUT();
;                     if (c + 1 < nch) DSA_GATHER(c + 1, g, 128);
	v_mov_b32_e32 v54, 0
	s_nop 1
	v_mov_b32_dpp v54, v53 row_bcast:31 row_mask:0xc bank_mask:0xf
	v_add_f32_e32 v53, v53, v54
	s_nop 0
	v_readlane_b32 s67, v53, 63
	s_nop 1
	v_div_scale_f32 v53, s[26:27], s67, s67, 1.0
	v_rcp_f32_e32 v54, v53
	s_nop 0
	v_fma_f32 v52, -v53, v54, 1.0
	v_fmac_f32_e32 v54, v52, v54
	v_div_scale_f32 v52, vcc, 1.0, s67, 1.0
	v_mul_f32_e32 v55, v52, v54
	v_fma_f32 v56, -v53, v55, v52
	v_fmac_f32_e32 v55, v56, v54
	v_fma_f32 v52, -v53, v55, v52
	v_bfe_u32 v53, v32, 16, 1
	v_add3_u32 v32, v32, v53, s80
	ds_write_b16_d16_hi v204, v32 offset:15360
	v_mul_f32_e32 v32, v33, v49
	v_bfe_u32 v33, v32, 16, 1
	v_add3_u32 v32, v32, v33, s80
	ds_write_b16_d16_hi v204, v32 offset:15872
	v_mul_f32_e32 v32, v34, v50
	v_div_fmas_f32 v52, v52, v54, v55
	v_bfe_u32 v33, v32, 16, 1
	v_div_fixup_f32 v52, v52, s67, 1.0
	v_add3_u32 v32, v32, v33, s80
	ds_write_b16_d16_hi v204, v32 offset:16384
	v_mul_f32_e32 v32, v39, v52
	v_bfe_u32 v33, v32, 16, 1
	v_add3_u32 v32, v32, v33, s80
	ds_write_b16_d16_hi v204, v32 offset:16896
	v_mul_f32_e32 v32, v36, v48
	v_bfe_u32 v33, v32, 16, 1
	v_add3_u32 v32, v32, v33, s80
	ds_write_b16_d16_hi v204, v32 offset:15488
	v_mul_f32_e32 v32, v37, v49
	v_bfe_u32 v33, v32, 16, 1
	v_add3_u32 v32, v32, v33, s80
	ds_write_b16_d16_hi v204, v32 offset:16000
	v_mul_f32_e32 v32, v38, v50
	v_bfe_u32 v33, v32, 16, 1
	v_add3_u32 v32, v32, v33, s80
	ds_write_b16_d16_hi v204, v32 offset:16512
	v_mul_f32_e32 v32, v43, v52
	v_bfe_u32 v33, v32, 16, 1
	v_add3_u32 v32, v32, v33, s80
	ds_write_b16_d16_hi v204, v32 offset:17024
	v_mul_f32_e32 v32, v40, v48
	v_bfe_u32 v33, v32, 16, 1
	v_add3_u32 v32, v32, v33, s80
	ds_write_b16_d16_hi v204, v32 offset:15616
	v_mul_f32_e32 v32, v41, v49
	v_bfe_u32 v33, v32, 16, 1
	v_add3_u32 v32, v32, v33, s80
	ds_write_b16_d16_hi v204, v32 offset:16128
	v_mul_f32_e32 v32, v42, v50
	v_bfe_u32 v33, v32, 16, 1
	v_add3_u32 v32, v32, v33, s80
	ds_write_b16_d16_hi v204, v32 offset:16640
	v_mul_f32_e32 v32, v47, v52
	v_bfe_u32 v33, v32, 16, 1
	v_add3_u32 v32, v32, v33, s80
	ds_write_b16_d16_hi v204, v32 offset:17152
	v_mul_f32_e32 v32, v44, v48
	v_bfe_u32 v33, v32, 16, 1
	v_add3_u32 v32, v32, v33, s80
	ds_write_b16_d16_hi v204, v32 offset:15744
	v_mul_f32_e32 v32, v45, v49
	v_bfe_u32 v33, v32, 16, 1
	v_add3_u32 v32, v32, v33, s80
	ds_write_b16_d16_hi v204, v32 offset:16256
	v_mul_f32_e32 v32, v46, v50
	v_bfe_u32 v33, v32, 16, 1
	v_add3_u32 v32, v32, v33, s80
	ds_write_b16_d16_hi v204, v32 offset:16768
	v_mul_f32_e32 v32, v51, v52
	v_bfe_u32 v33, v32, 16, 1
	v_add3_u32 v32, v32, v33, s80
	ds_write_b16_d16_hi v204, v32 offset:17280
	s_and_b64 vcc, exec, s[18:19]
	v_mov_b32_e32 v34, 0
	v_mov_b32_e32 v33, 0
	v_mov_b32_e32 v32, 0
	v_mov_b32_e32 v56, 0
	v_mov_b32_e32 v55, 0
	v_mov_b32_e32 v54, 0
	v_mov_b32_e32 v53, 0
	v_mov_b32_e32 v52, 0
	v_mov_b32_e32 v51, 0
	v_mov_b32_e32 v50, 0
	v_mov_b32_e32 v49, 0
	v_mov_b32_e32 v48, 0
	v_mov_b32_e32 v47, 0
	v_mov_b32_e32 v46, 0
	v_mov_b32_e32 v45, 0
	v_mov_b32_e32 v44, 0
	v_mov_b32_e32 v43, 0
	v_mov_b32_e32 v42, 0
	v_mov_b32_e32 v41, 0
	v_mov_b32_e32 v40, 0
	v_mov_b32_e32 v39, 0
	v_mov_b32_e32 v38, 0
	v_mov_b32_e32 v37, 0
	v_mov_b32_e32 v36, 0
	s_cbranch_vccnz .LBB0_1181
	s_lshl_b32 s18, s65, 1
	s_add_u32 s18, s48, s18
	s_addc_u32 s19, s49, 0
	v_mov_b32_e32 v65, v139
	v_mov_b32_e32 v36, 0
	v_lshl_add_u64 v[72:73], s[18:19], 0, v[64:65]
	s_mov_b32 s26, 0
	s_mov_b32 s27, 0
	v_mov_b32_e32 v37, v36
	v_mov_b32_e32 v38, v36
	v_mov_b32_e32 v39, v36
	v_mov_b32_e32 v40, v36
	v_mov_b32_e32 v41, v36
	v_mov_b32_e32 v42, v36
	v_mov_b32_e32 v43, v36
	v_mov_b32_e32 v44, v36
	v_mov_b32_e32 v45, v36
	v_mov_b32_e32 v46, v36
	v_mov_b32_e32 v47, v36
	v_mov_b32_e32 v48, v36
	v_mov_b32_e32 v49, v36
	v_mov_b32_e32 v50, v36
	v_mov_b32_e32 v51, v36
	v_mov_b32_e32 v52, v36
	v_mov_b32_e32 v53, v36
	v_mov_b32_e32 v54, v36
	v_mov_b32_e32 v55, v36
	v_mov_b32_e32 v56, v36
	v_mov_b32_e32 v57, v36
	v_mov_b32_e32 v58, v36
	v_mov_b32_e32 v59, v36
	v_mov_b32_e32 v60, v36
	v_mov_b32_e32 v61, v36
	v_mov_b32_e32 v62, v36
	v_mov_b32_e32 v63, v36
	v_mov_b32_e32 v32, v36
	v_mov_b32_e32 v33, v36
	v_mov_b32_e32 v34, v36
	v_mov_b32_e32 v35, v36
	s_cmp_gt_i32 s64, 1
	s_cbranch_scc0 .Lpv_A
	v_add_u32_e32 v94, s26, v76
	ds_read_u16 v95, v94
	ds_read_u16 v96, v94 offset:8
	ds_read_u16 v102, v94 offset:16
	ds_read_u16 v104, v94 offset:24
	ds_read_u16 v110, v94 offset:32
	ds_read_u16 v112, v94 offset:40
	ds_read_u16 v118, v94 offset:48
	ds_read_u16 v120, v94 offset:56
	s_waitcnt lgkmcnt(7)
	v_lshlrev_b32_e32 v138, 10, v95
	v_lshl_add_u64 v[94:95], v[72:73], 0, v[138:139]
	s_waitcnt lgkmcnt(6)
	v_lshlrev_b32_e32 v138, 10, v96
	v_lshl_add_u64 v[98:99], v[72:73], 0, v[138:139]
	s_waitcnt lgkmcnt(5)
	v_lshlrev_b32_e32 v138, 10, v102
	v_lshl_add_u64 v[102:103], v[72:73], 0, v[138:139]
	s_waitcnt lgkmcnt(4)
	v_lshlrev_b32_e32 v138, 10, v104
	v_lshl_add_u64 v[106:107], v[72:73], 0, v[138:139]
	s_waitcnt lgkmcnt(3)
	v_lshlrev_b32_e32 v138, 10, v110
	v_lshl_add_u64 v[110:111], v[72:73], 0, v[138:139]
	s_waitcnt lgkmcnt(2)
	v_lshlrev_b32_e32 v138, 10, v112
	v_lshl_add_u64 v[114:115], v[72:73], 0, v[138:139]
	s_waitcnt lgkmcnt(1)
	v_lshlrev_b32_e32 v138, 10, v118
	v_lshl_add_u64 v[118:119], v[72:73], 0, v[138:139]
	s_waitcnt lgkmcnt(0)
	v_lshlrev_b32_e32 v138, 10, v120
	v_lshl_add_u64 v[122:123], v[72:73], 0, v[138:139]
	global_load_dwordx4 v[94:97], v[94:95], off offset:256
	s_nop 0
	global_load_dwordx4 v[98:101], v[98:99], off offset:256
	s_nop 0
	global_load_dwordx4 v[102:105], v[102:103], off offset:256
	s_nop 0
	global_load_dwordx4 v[106:109], v[106:107], off offset:256
	s_nop 0
	global_load_dwordx4 v[110:113], v[110:111], off offset:256
	s_nop 0
	global_load_dwordx4 v[114:117], v[114:115], off offset:256
	s_nop 0
	global_load_dwordx4 v[118:121], v[118:119], off offset:256
	s_nop 0
	global_load_dwordx4 v[122:125], v[122:123], off offset:256
; #define LAS __attribute__((address_space(3)))
; #define DSA_GATHER(c, g_, off_) do { _Pragma("unroll") for (int i = 0; i < 8; ++i) { const unsigned kidx = ixl[(c) * 32 + kq + 4 * i]; \
;                 gr[i] = *(const u32x4*)(KV2 + ((size_t)kidx * 2 + (g_)) * 256 + (off_) + 8 * col); } } while (0)
; #define DSA_PUT() do { _Pragma("unroll") for (int i = 0; i < 8; ++i) *(LAS u32x4*)(vst + (kq + 4 * i) * 272 + col * 16) = gr[i]; } while (0)
; __device__ __forceinline__ void dsa_phase(Frame& F) {
;     ...
;                 for (int c = 0; c < nch; ++c) {
;                     DSA_PUT();
;                     if (c + 1 < nch) DSA_GATHER(c + 1, g, 128);
;                     bf16x8 pf = (bf16x8){0, 0, 0, 0, 0, 0, 0, 0};
;                     if (col < 4) pf = *(const LAS bf16x8*)(Pb + col * 256 + 32 * c + 8 * kq);
.Lpv_A:
	s_add_i32 s27, s27, 1
	v_add_u32_e32 v64, v205, v207
	s_cmp_lt_i32 s27, s64
	s_cbranch_scc0 .Lpv_A_last
	s_waitcnt vmcnt(15)
	ds_write_b128 v64, v[0:3]
	s_waitcnt vmcnt(14)
	ds_write_b128 v64, v[4:7] offset:1088
	s_waitcnt vmcnt(13)
	ds_write_b128 v64, v[8:11] offset:2176
	s_waitcnt vmcnt(12)
	ds_write_b128 v64, v[12:15] offset:3264
	s_waitcnt vmcnt(11)
	ds_write_b128 v64, v[16:19] offset:4352
	s_waitcnt vmcnt(10)
	ds_write_b128 v64, v[20:23] offset:5440
	s_waitcnt vmcnt(9)
	ds_write_b128 v64, v[24:27] offset:6528
	s_waitcnt vmcnt(8)
	ds_write_b128 v64, v[28:31] offset:7616
	s_add_i32 s18, s27, 1
	s_cmp_lt_i32 s18, s64
	s_cbranch_scc0 .Lpv_A_c
	v_add_u32_e32 v0, s26, v76
	ds_read_u16 v1, v0 offset:64
	ds_read_u16 v2, v0 offset:72
	ds_read_u16 v8, v0 offset:80
	ds_read_u16 v10, v0 offset:88
	ds_read_u16 v16, v0 offset:96
	ds_read_u16 v18, v0 offset:104
	ds_read_u16 v24, v0 offset:112
	ds_read_u16 v26, v0 offset:120
	s_waitcnt lgkmcnt(7)
	v_lshlrev_b32_e32 v138, 10, v1
	v_lshl_add_u64 v[0:1], v[72:73], 0, v[138:139]
	s_waitcnt lgkmcnt(6)
	v_lshlrev_b32_e32 v138, 10, v2
	v_lshl_add_u64 v[4:5], v[72:73], 0, v[138:139]
	s_waitcnt lgkmcnt(5)
	v_lshlrev_b32_e32 v138, 10, v8
	v_lshl_add_u64 v[8:9], v[72:73], 0, v[138:139]
	s_waitcnt lgkmcnt(4)
	v_lshlrev_b32_e32 v138, 10, v10
	v_lshl_add_u64 v[12:13], v[72:73], 0, v[138:139]
	s_waitcnt lgkmcnt(3)
	v_lshlrev_b32_e32 v138, 10, v16
	v_lshl_add_u64 v[16:17], v[72:73], 0, v[138:139]
	s_waitcnt lgkmcnt(2)
	v_lshlrev_b32_e32 v138, 10, v18
	v_lshl_add_u64 v[20:21], v[72:73], 0, v[138:139]
	s_waitcnt lgkmcnt(1)
	v_lshlrev_b32_e32 v138, 10, v24
	v_lshl_add_u64 v[24:25], v[72:73], 0, v[138:139]
	s_waitcnt lgkmcnt(0)
	v_lshlrev_b32_e32 v138, 10, v26
	v_lshl_add_u64 v[28:29], v[72:73], 0, v[138:139]
	global_load_dwordx4 v[0:3], v[0:1], off offset:256
	s_nop 0
	global_load_dwordx4 v[4:7], v[4:5], off offset:256
	s_nop 0
	global_load_dwordx4 v[8:11], v[8:9], off offset:256
	s_nop 0
	global_load_dwordx4 v[12:15], v[12:13], off offset:256
	s_nop 0
	global_load_dwordx4 v[16:19], v[16:17], off offset:256
	s_nop 0
	global_load_dwordx4 v[20:23], v[20:21], off offset:256
	s_nop 0
	global_load_dwordx4 v[24:27], v[24:25], off offset:256
	s_nop 0
	global_load_dwordx4 v[28:31], v[28:29], off offset:256
	s_branch .Lpv_A_c
.Lpv_A_last:
	s_waitcnt vmcnt(7)
	ds_write_b128 v64, v[0:3]
	s_waitcnt vmcnt(6)
	ds_write_b128 v64, v[4:7] offset:1088
	s_waitcnt vmcnt(5)
	ds_write_b128 v64, v[8:11] offset:2176
	s_waitcnt vmcnt(4)
	ds_write_b128 v64, v[12:15] offset:3264
	s_waitcnt vmcnt(3)
	ds_write_b128 v64, v[16:19] offset:4352
	s_waitcnt vmcnt(2)
	ds_write_b128 v64, v[20:23] offset:5440
	s_waitcnt vmcnt(1)
	ds_write_b128 v64, v[24:27] offset:6528
	s_waitcnt vmcnt(0)
	ds_write_b128 v64, v[28:31] offset:7616
.Lpv_A_c:
	v_mov_b32_e32 v64, 0
	v_mov_b32_e32 v65, 0
	v_mov_b32_e32 v66, 0
	v_mov_b32_e32 v67, 0
	s_and_saveexec_b64 s[18:19], s[8:9]
	s_cbranch_execz .Lpv_A_m
	v_add_u32_e32 v64, s26, v194
	ds_read_b128 v[64:67], v64
; #define LAS __attribute__((address_space(3)))
; #define DSA_GATHER(c, g_, off_) do { _Pragma("unroll") for (int i = 0; i < 8; ++i) { const unsigned kidx = ixl[(c) * 32 + kq + 4 * i]; \
;                 gr[i] = *(const u32x4*)(KV2 + ((size_t)kidx * 2 + (g_)) * 256 + (off_) + 8 * col); } } while (0)
; #define DSA_PUT() do { _Pragma("unroll") for (int i = 0; i < 8; ++i) *(LAS u32x4*)(vst + (kq + 4 * i) * 272 + col * 16) = gr[i]; } while (0)
; __device__ __forceinline__ void dsa_phase(Frame& F) {
;     ...
;                 for (int c = 0; c < nch; ++c) {
;                     DSA_PUT();
;                     if (c + 1 < nch) DSA_GATHER(c + 1, g, 128);
;                     bf16x8 pf = (bf16x8){0, 0, 0, 0, 0, 0, 0, 0};
;                     if (col < 4) pf = *(const LAS bf16x8*)(Pb + col * 256 + 32 * c + 8 * kq);
;                     const LAS unsigned char* vrow = vst + (8 * kq + tq) * 272 + 8 * tp;
; #pragma unroll
;                     for (int db = 0; db < 8; ++db) {
;                         const v4i16_t lo = __builtin_amdgcn_ds_read_tr16_b64_v4i16((LAS v4i16_t*)(vrow + 32 * db));
;                         const v4i16_t hi = __builtin_amdgcn_ds_read_tr16_b64_v4i16((LAS v4i16_t*)(vrow + 4 * 272 + 32 * db));
;                         const bf16x8 vf = {lo[0], lo[1], lo[2], lo[3], hi[0], hi[1], hi[2], hi[3]};
;                         oacc[db] = __builtin_amdgcn_mfma_f32_16x16x32_bf16(vf, pf, oacc[db], 0, 0, 0);
;                     }
.Lpv_A_m:
	s_or_b64 exec, exec, s[18:19]
	ds_read_b64_tr_b16 v[78:79], v214
	ds_read_b64_tr_b16 v[80:81], v214 offset:1088
	ds_read_b64_tr_b16 v[84:85], v214 offset:1120
	ds_read_b64_tr_b16 v[82:83], v214 offset:32
	ds_read_b64_tr_b16 v[86:87], v214 offset:64
	ds_read_b64_tr_b16 v[90:91], v214 offset:96
	ds_read_b64_tr_b16 v[88:89], v214 offset:1152
	ds_read_b64_tr_b16 v[92:93], v214 offset:1184
	s_waitcnt lgkmcnt(6)
	v_mfma_f32_16x16x32_bf16 v[32:35], v[78:81], v[64:67], v[32:35]
	ds_read_b64_tr_b16 v[78:79], v214 offset:128
	ds_read_b64_tr_b16 v[80:81], v214 offset:1216
	s_add_i32 s26, s26, 64
	s_cmp_eq_u32 s64, s27
	s_waitcnt lgkmcnt(6)
	v_mfma_f32_16x16x32_bf16 v[60:63], v[82:85], v[64:67], v[60:63]
	s_waitcnt lgkmcnt(3)
	v_mfma_f32_16x16x32_bf16 v[56:59], v[86:89], v[64:67], v[56:59]
	s_waitcnt lgkmcnt(2)
	v_mfma_f32_16x16x32_bf16 v[52:55], v[90:93], v[64:67], v[52:55]
	ds_read_b64_tr_b16 v[84:85], v214 offset:1248
	ds_read_b64_tr_b16 v[82:83], v214 offset:160
	ds_read_b64_tr_b16 v[86:87], v214 offset:192
	ds_read_b64_tr_b16 v[90:91], v214 offset:224
	ds_read_b64_tr_b16 v[88:89], v214 offset:1280
	ds_read_b64_tr_b16 v[92:93], v214 offset:1312
	s_waitcnt lgkmcnt(6)
	v_mfma_f32_16x16x32_bf16 v[48:51], v[78:81], v[64:67], v[48:51]
	s_waitcnt lgkmcnt(4)
	v_mfma_f32_16x16x32_bf16 v[44:47], v[82:85], v[64:67], v[44:47]
	s_waitcnt lgkmcnt(1)
	v_mfma_f32_16x16x32_bf16 v[40:43], v[86:89], v[64:67], v[40:43]
	s_waitcnt lgkmcnt(0)
	v_mfma_f32_16x16x32_bf16 v[36:39], v[90:93], v[64:67], v[36:39]
	s_cbranch_scc1 .LBB0_1181
.Lpv_B:
	s_add_i32 s27, s27, 1
	v_add_u32_e32 v64, v205, v207
	s_cmp_lt_i32 s27, s64
	s_cbranch_scc0 .Lpv_B_last
	s_waitcnt vmcnt(15)
	ds_write_b128 v64, v[94:97]
	s_waitcnt vmcnt(14)
	ds_write_b128 v64, v[98:101] offset:1088
	s_waitcnt vmcnt(13)
	ds_write_b128 v64, v[102:105] offset:2176
	s_waitcnt vmcnt(12)
	ds_write_b128 v64, v[106:109] offset:3264
	s_waitcnt vmcnt(11)
	ds_write_b128 v64, v[110:113] offset:4352
	s_waitcnt vmcnt(10)
	ds_write_b128 v64, v[114:117] offset:5440
	s_waitcnt vmcnt(9)
	ds_write_b128 v64, v[118:121] offset:6528
	s_waitcnt vmcnt(8)
	ds_write_b128 v64, v[122:125] offset:7616
	s_add_i32 s18, s27, 1
	s_cmp_lt_i32 s18, s64
	s_cbranch_scc0 .Lpv_B_c
	v_add_u32_e32 v94, s26, v76
	ds_read_u16 v95, v94 offset:64
	ds_read_u16 v96, v94 offset:72
	ds_read_u16 v102, v94 offset:80
	ds_read_u16 v104, v94 offset:88
	ds_read_u16 v110, v94 offset:96
	ds_read_u16 v112, v94 offset:104
	ds_read_u16 v118, v94 offset:112
	ds_read_u16 v120, v94 offset:120
	s_waitcnt lgkmcnt(7)
	v_lshlrev_b32_e32 v138, 10, v95
	v_lshl_add_u64 v[94:95], v[72:73], 0, v[138:139]
	s_waitcnt lgkmcnt(6)
	v_lshlrev_b32_e32 v138, 10, v96
	v_lshl_add_u64 v[98:99], v[72:73], 0, v[138:139]
	s_waitcnt lgkmcnt(5)
	v_lshlrev_b32_e32 v138, 10, v102
	v_lshl_add_u64 v[102:103], v[72:73], 0, v[138:139]
	s_waitcnt lgkmcnt(4)
	v_lshlrev_b32_e32 v138, 10, v104
	v_lshl_add_u64 v[106:107], v[72:73], 0, v[138:139]
	s_waitcnt lgkmcnt(3)
	v_lshlrev_b32_e32 v138, 10, v110
	v_lshl_add_u64 v[110:111], v[72:73], 0, v[138:139]
	s_waitcnt lgkmcnt(2)
	v_lshlrev_b32_e32 v138, 10, v112
	v_lshl_add_u64 v[114:115], v[72:73], 0, v[138:139]
	s_waitcnt lgkmcnt(1)
	v_lshlrev_b32_e32 v138, 10, v118
	v_lshl_add_u64 v[118:119], v[72:73], 0, v[138:139]
	s_waitcnt lgkmcnt(0)
	v_lshlrev_b32_e32 v138, 10, v120
	v_lshl_add_u64 v[122:123], v[72:73], 0, v[138:139]
	global_load_dwordx4 v[94:97], v[94:95], off offset:256
	s_nop 0
	global_load_dwordx4 v[98:101], v[98:99], off offset:256
	s_nop 0
	global_load_dwordx4 v[102:105], v[102:103], off offset:256
	s_nop 0
	global_load_dwordx4 v[106:109], v[106:107], off offset:256
	s_nop 0
	global_load_dwordx4 v[110:113], v[110:111], off offset:256
	s_nop 0
	global_load_dwordx4 v[114:117], v[114:115], off offset:256
	s_nop 0
	global_load_dwordx4 v[118:121], v[118:119], off offset:256
	s_nop 0
	global_load_dwordx4 v[122:125], v[122:123], off offset:256
	s_branch .Lpv_B_c
.Lpv_B_last:
	s_waitcnt vmcnt(7)
	ds_write_b128 v64, v[94:97]
	s_waitcnt vmcnt(6)
	ds_write_b128 v64, v[98:101] offset:1088
	s_waitcnt vmcnt(5)
	ds_write_b128 v64, v[102:105] offset:2176
	s_waitcnt vmcnt(4)
	ds_write_b128 v64, v[106:109] offset:3264
	s_waitcnt vmcnt(3)
	ds_write_b128 v64, v[110:113] offset:4352
	s_waitcnt vmcnt(2)
	ds_write_b128 v64, v[114:117] offset:5440
	s_waitcnt vmcnt(1)
	ds_write_b128 v64, v[118:121] offset:6528
	s_waitcnt vmcnt(0)
	ds_write_b128 v64, v[122:125] offset:7616

; #define LAS __attribute__((address_space(3)))
; __device__ __forceinline__ void dsa_phase(Frame& F) {
;     ...
;                     if (col < 4) pf = *(const LAS bf16x8*)(Pb + col * 256 + 32 * c + 8 * kq);
;                     const LAS unsigned char* vrow = vst + (8 * kq + tq) * 272 + 8 * tp;
; #pragma unroll
;                     for (int db = 0; db < 8; ++db) {
;                         const v4i16_t lo = __builtin_amdgcn_ds_read_tr16_b64_v4i16((LAS v4i16_t*)(vrow + 32 * db));
;                         const v4i16_t hi = __builtin_amdgcn_ds_read_tr16_b64_v4i16((LAS v4i16_t*)(vrow + 4 * 272 + 32 * db));
;                         const bf16x8 vf = {lo[0], lo[1], lo[2], lo[3], hi[0], hi[1], hi[2], hi[3]};
;                         oacc[db] = __builtin_amdgcn_mfma_f32_16x16x32_bf16(vf, pf, oacc[db], 0, 0, 0);
;                     }
.Lpv_B_m:
	s_or_b64 exec, exec, s[18:19]
	ds_read_b64_tr_b16 v[78:79], v214
	ds_read_b64_tr_b16 v[80:81], v214 offset:1088
	ds_read_b64_tr_b16 v[84:85], v214 offset:1120
	ds_read_b64_tr_b16 v[82:83], v214 offset:32
	ds_read_b64_tr_b16 v[86:87], v214 offset:64
	ds_read_b64_tr_b16 v[90:91], v214 offset:96
	ds_read_b64_tr_b16 v[88:89], v214 offset:1152
	ds_read_b64_tr_b16 v[92:93], v214 offset:1184
	s_waitcnt lgkmcnt(6)
	v_mfma_f32_16x16x32_bf16 v[32:35], v[78:81], v[64:67], v[32:35]
	ds_read_b64_tr_b16 v[78:79], v214 offset:128
	ds_read_b64_tr_b16 v[80:81], v214 offset:1216
	s_add_i32 s26, s26, 64
	s_cmp_eq_u32 s64, s27
	s_waitcnt lgkmcnt(6)
	v_mfma_f32_16x16x32_bf16 v[60:63], v[82:85], v[64:67], v[60:63]
	s_waitcnt lgkmcnt(3)
	v_mfma_f32_16x16x32_bf16 v[56:59], v[86:89], v[64:67], v[56:59]
	s_waitcnt lgkmcnt(2)
	v_mfma_f32_16x16x32_bf16 v[52:55], v[90:93], v[64:67], v[52:55]
	ds_read_b64_tr_b16 v[84:85], v214 offset:1248
	ds_read_b64_tr_b16 v[82:83], v214 offset:160
	ds_read_b64_tr_b16 v[86:87], v214 offset:192
	ds_read_b64_tr_b16 v[90:91], v214 offset:224
	ds_read_b64_tr_b16 v[88:89], v214 offset:1280
	ds_read_b64_tr_b16 v[92:93], v214 offset:1312
	s_waitcnt lgkmcnt(6)
	v_mfma_f32_16x16x32_bf16 v[48:51], v[78:81], v[64:67], v[48:51]
	s_waitcnt lgkmcnt(4)
	v_mfma_f32_16x16x32_bf16 v[44:47], v[82:85], v[64:67], v[44:47]
	s_waitcnt lgkmcnt(1)
	v_mfma_f32_16x16x32_bf16 v[40:43], v[86:89], v[64:67], v[40:43]
	s_waitcnt lgkmcnt(0)
	v_mfma_f32_16x16x32_bf16 v[36:39], v[90:93], v[64:67], v[36:39]
	s_cbranch_scc1 .LBB0_1181
	s_branch .Lpv_A
